# slow (bias/causal) softmax path also runs at raised priority
# baseline (speedup 1.0000x reference)
; __device__ __forceinline__ float fexp2(float x) { return __builtin_amdgcn_exp2f(x); }
; template <int MODE, int DK, bool PASS2> ...
;     ...
; #pragma unroll
;                     for (int r = 0; r < 16; ++r) { s0[r] *= sl2; s1[r] *= sl2; }
;                     if (need_bias || need_causal || need_win) {
; #pragma unroll
;                         for (int i = 0; i < 32; ++i) {
;                             const int s = kv0 + (i >> 3) * 16 + 8 * g + (i & 7);
;                             const int dist = t_lane - ((MODE == M_CMP) ? 16 * s + 31 : s);
;                             float v = (i < 16) ? s0[i & 15] : s1[i & 15];
;                             if (need_bias) { const int di = dist < 0 ? 0 : (dist > 128 ? 128 : dist); v += tb[di]; }
;                             bool msk = dist < 0;
;                             if (MODE == M_WIN) msk = msk || dist >= 512;
;                             if (msk) v = NEG;
;                             if (i < 16) s0[i & 15] = v; else s1[i & 15] = v;
;                             if ((i & 7) == 7) __builtin_amdgcn_sched_barrier(0);
;                         }
;                     }
;                     if (MODE == M_SLC) {
;                         if (!selbit) {
; #pragma unroll
;                             for (int r = 0; r < 16; ++r) { s0[r] = NEG; s1[r] = NEG; }
;                         }
;                     }
;                     if (!PASS2) {
;                         float mx = fmaxf(s0[0], s1[0]);
; #pragma unroll
;                         for (int r = 1; r < 16; ++r) mx = fmax3(mx, s0[r], s1[r]);
;                         mx = xhalf_max(mx);
;                         const float mn = (mx > m_run + 8.0f) ? mx : m_run;
;                         const float alpha = fexp2(m_run - mn);
;                         m_run = mn;
;                         float ps0 = 0.f, ps1 = 0.f;
; #pragma unroll
;                         for (int r = 0; r < 16; ++r) { s0[r] = fexp2(s0[r] - mn); s1[r] = fexp2(s1[r] - mn); ps0 += s0[r]; ps1 += s1[r]; }
;                         l_run = l_run * alpha + (ps0 + ps1);
;                         if (__builtin_amdgcn_ballot_w64(alpha != 1.0f) != 0ull) {
; #pragma unroll
;                             for (int db = 0; db < 4; ++db)
; #pragma unroll
;                                 for (int r = 0; r < 16; ++r) O[db][r] *= alpha;
;                         }
.LBB0_947:
	s_andn2_saveexec_b64 s[52:53], s[52:53]
	s_cbranch_execz .LBB0_951
	s_setprio 1
	s_nop 1
	v_mul_f32_e32 v7, 0x3e0293ee, v101
	v_mul_f32_e32 v101, 0x3e0293ee, v108
	v_add_u32_e32 v108, s87, v228
	v_subrev_u32_e32 v12, 63, v108
	v_mul_f32_e32 v4, 0x3e0293ee, v98
	v_cmp_ge_i32_e32 vcc, v198, v12
	v_mul_f32_e32 v5, 0x3e0293ee, v99
	v_mul_f32_e32 v114, 0x3e0293ee, v84
	v_cndmask_b32_e32 v84, v215, v4, vcc
	v_cmp_gt_i32_e32 vcc, v198, v12
	v_subrev_u32_e32 v4, 61, v108
	v_mul_f32_e32 v99, 0x3e0293ee, v83
	v_mul_f32_e32 v6, 0x3e0293ee, v100
	v_cndmask_b32_e32 v83, v215, v5, vcc
	v_cmp_ge_i32_e32 vcc, v198, v4
	v_subrev_u32_e32 v4, 60, v108
	v_mul_f32_e32 v98, 0x3e0293ee, v82
	v_cndmask_b32_e32 v82, v215, v6, vcc
	v_cmp_ge_i32_e32 vcc, v198, v4
	v_subrev_u32_e32 v4, 59, v108
	v_mul_f32_e32 v8, 0x3e0293ee, v102
	v_cndmask_b32_e32 v17, v215, v7, vcc
	v_cmp_ge_i32_e32 vcc, v198, v4
	v_subrev_u32_e32 v4, 58, v108
	v_mul_f32_e32 v9, 0x3e0293ee, v103
	v_cndmask_b32_e32 v16, v215, v8, vcc
	v_cmp_ge_i32_e32 vcc, v198, v4
	v_subrev_u32_e32 v4, 57, v108
	v_mul_f32_e32 v10, 0x3e0293ee, v104
	v_cndmask_b32_e32 v15, v215, v9, vcc
	v_cmp_ge_i32_e32 vcc, v198, v4
	v_subrev_u32_e32 v4, 56, v108
	v_mul_f32_e32 v11, 0x3e0293ee, v105
	v_cndmask_b32_e32 v14, v215, v10, vcc
	v_cmp_ge_i32_e32 vcc, v198, v4
	v_mul_f32_e32 v85, 0x3e0293ee, v85
	v_mul_f32_e32 v86, 0x3e0293ee, v86
	v_mul_f32_e32 v87, 0x3e0293ee, v87
	v_mul_f32_e32 v88, 0x3e0293ee, v88
	v_mul_f32_e32 v89, 0x3e0293ee, v89
	v_mul_f32_e32 v13, 0x3e0293ee, v106
	v_mul_f32_e32 v90, 0x3e0293ee, v90
	v_mul_f32_e32 v100, 0x3e0293ee, v107
	v_mul_f32_e32 v91, 0x3e0293ee, v91
	v_mul_f32_e32 v102, 0x3e0293ee, v92
	v_mul_f32_e32 v92, 0x3e0293ee, v109
	v_mul_f32_e32 v103, 0x3e0293ee, v93
	v_mul_f32_e32 v93, 0x3e0293ee, v110
	v_mul_f32_e32 v104, 0x3e0293ee, v94
	v_mul_f32_e32 v94, 0x3e0293ee, v111
	v_mul_f32_e32 v105, 0x3e0293ee, v95
	v_mul_f32_e32 v95, 0x3e0293ee, v112
	v_mul_f32_e32 v106, 0x3e0293ee, v96
	v_mul_f32_e32 v96, 0x3e0293ee, v113
	v_cndmask_b32_e32 v12, v215, v11, vcc
	v_mul_f32_e32 v107, 0x3e0293ee, v97
	v_subrev_u32_e32 v4, 47, v108
	v_cmp_ge_i32_e32 vcc, v198, v4
	v_subrev_u32_e32 v4, 46, v108
	s_nop 0
	v_cndmask_b32_e32 v13, v215, v13, vcc
	v_cmp_ge_i32_e32 vcc, v198, v4
	v_subrev_u32_e32 v4, 45, v108
	s_nop 0
	v_cndmask_b32_e32 v11, v215, v100, vcc
	v_cmp_ge_i32_e32 vcc, v198, v4
	v_subrev_u32_e32 v4, 44, v108
	s_nop 0
	v_cndmask_b32_e32 v10, v215, v101, vcc
	v_cmp_ge_i32_e32 vcc, v198, v4
	v_subrev_u32_e32 v4, 43, v108
	s_nop 0
	v_cndmask_b32_e32 v9, v215, v92, vcc
	v_cmp_ge_i32_e32 vcc, v198, v4
	v_subrev_u32_e32 v4, 42, v108
	s_nop 0
	v_cndmask_b32_e32 v8, v215, v93, vcc
	v_cmp_ge_i32_e32 vcc, v198, v4
	v_subrev_u32_e32 v4, 41, v108
	s_nop 0
	v_cndmask_b32_e32 v7, v215, v94, vcc
	v_cmp_ge_i32_e32 vcc, v198, v4
	v_subrev_u32_e32 v4, 40, v108
	s_nop 0
	v_cndmask_b32_e32 v6, v215, v95, vcc
	v_cmp_ge_i32_e32 vcc, v198, v4
	s_nop 1
	v_cndmask_b32_e32 v5, v215, v96, vcc
	v_subrev_u32_e32 v4, 31, v108
	v_cmp_ge_i32_e32 vcc, v198, v4
	v_subrev_u32_e32 v4, 30, v108
	s_nop 0
	v_cndmask_b32_e32 v100, v215, v98, vcc
	v_cmp_ge_i32_e32 vcc, v198, v4
	v_subrev_u32_e32 v4, 29, v108
	s_nop 0
	v_cndmask_b32_e32 v99, v215, v99, vcc
	v_cmp_ge_i32_e32 vcc, v198, v4
	v_subrev_u32_e32 v4, 28, v108
	s_nop 0
	v_cndmask_b32_e32 v98, v215, v114, vcc
	v_cmp_ge_i32_e32 vcc, v198, v4
	v_subrev_u32_e32 v4, 27, v108
	s_nop 0
	v_cndmask_b32_e32 v97, v215, v85, vcc
	v_cmp_ge_i32_e32 vcc, v198, v4
	v_subrev_u32_e32 v4, 26, v108
	s_nop 0
	v_cndmask_b32_e32 v96, v215, v86, vcc
	v_cmp_ge_i32_e32 vcc, v198, v4
	v_subrev_u32_e32 v4, 25, v108
	s_nop 0
	v_cndmask_b32_e32 v95, v215, v87, vcc
	v_cmp_ge_i32_e32 vcc, v198, v4
	v_subrev_u32_e32 v4, 24, v108
	s_nop 0
	v_cndmask_b32_e32 v94, v215, v88, vcc
	v_cmp_ge_i32_e32 vcc, v198, v4
	s_nop 1
	v_cndmask_b32_e32 v92, v215, v89, vcc
	v_add_u32_e32 v4, -15, v108
	v_cmp_ge_i32_e32 vcc, v198, v4
	v_add_u32_e32 v4, -14, v108
	s_nop 0
	v_cndmask_b32_e32 v93, v215, v90, vcc
	v_cmp_ge_i32_e32 vcc, v198, v4
	v_add_u32_e32 v4, -13, v108
	s_nop 0
	v_cndmask_b32_e32 v91, v215, v91, vcc
	v_cmp_ge_i32_e32 vcc, v198, v4
	v_add_u32_e32 v4, -12, v108
	s_nop 0
	v_cndmask_b32_e32 v90, v215, v102, vcc
	v_cmp_ge_i32_e32 vcc, v198, v4
	v_add_u32_e32 v4, -11, v108
	s_nop 0
	v_cndmask_b32_e32 v89, v215, v103, vcc
	v_cmp_ge_i32_e32 vcc, v198, v4
	v_add_u32_e32 v4, -10, v108
	s_nop 0
	v_cndmask_b32_e32 v88, v215, v104, vcc
	v_cmp_ge_i32_e32 vcc, v198, v4
	v_add_u32_e32 v4, -9, v108
	s_nop 0
	v_cndmask_b32_e32 v87, v215, v105, vcc
	v_cmp_ge_i32_e32 vcc, v198, v4
	v_add_u32_e32 v4, -8, v108
	s_nop 0
	v_cndmask_b32_e32 v86, v215, v106, vcc
	v_cmp_ge_i32_e32 vcc, v198, v4
	s_nop 1
	v_cndmask_b32_e32 v85, v215, v107, vcc
	v_max_f32_e32 v4, v84, v100
	v_max3_f32 v4, v4, v83, v99
	s_nop 0
	v_max3_f32 v4, v4, v82, v98
	s_nop 0
	v_max3_f32 v4, v4, v17, v97
	s_nop 0
	v_max3_f32 v4, v4, v16, v96
	s_nop 0
	v_max3_f32 v4, v4, v15, v95
	s_nop 0
	v_max3_f32 v4, v4, v14, v94
	s_nop 0
	v_max3_f32 v4, v4, v12, v92
	s_nop 0
	v_max3_f32 v4, v4, v13, v93
	s_nop 0
	v_max3_f32 v4, v4, v11, v91
	s_nop 0
	v_max3_f32 v4, v4, v10, v90
	s_nop 0
	v_max3_f32 v4, v4, v9, v89
	s_nop 0
	v_max3_f32 v4, v4, v8, v88
	s_nop 0
	v_max3_f32 v4, v4, v7, v87
	s_nop 0
	v_max3_f32 v4, v4, v6, v86
	s_nop 0
	v_max3_f32 v4, v4, v5, v85
	s_nop 0
	v_mov_b32_e32 v101, v4
	s_nop 1
	v_permlane32_swap_b32_e32 v4, v101
	v_max_f32_e32 v101, v101, v101
	v_max_f32_e32 v4, v4, v4
	v_max_f32_e32 v4, v4, v101
	v_cmp_gt_f32_e32 vcc, v4, v2
	s_nop 1
	v_cndmask_b32_e32 v4, v239, v4, vcc
	v_sub_f32_e32 v2, v239, v4
	v_exp_f32_e32 v2, v2
	s_nop 0
	v_cmp_neq_f32_e32 vcc, 1.0, v2
	s_cbranch_vccz .LBB0_950
; template <int MODE, int DK, bool PASS2> ...
;     ...
;                         if (__builtin_amdgcn_ballot_w64(alpha != 1.0f) != 0ull) {
; #pragma unroll
;                             for (int db = 0; db < 4; ++db)
; #pragma unroll
;                                 for (int r = 0; r < 16; ++r) O[db][r] *= alpha;
;                         }
	v_pk_mul_f32 v[80:81], v[80:81], v[2:3] op_sel_hi:[1,0]
	v_pk_mul_f32 v[78:79], v[78:79], v[2:3] op_sel_hi:[1,0]
	v_pk_mul_f32 v[76:77], v[76:77], v[2:3] op_sel_hi:[1,0]
	v_pk_mul_f32 v[74:75], v[74:75], v[2:3] op_sel_hi:[1,0]
	v_pk_mul_f32 v[72:73], v[72:73], v[2:3] op_sel_hi:[1,0]
	v_pk_mul_f32 v[70:71], v[70:71], v[2:3] op_sel_hi:[1,0]
	v_pk_mul_f32 v[68:69], v[68:69], v[2:3] op_sel_hi:[1,0]
	v_pk_mul_f32 v[66:67], v[66:67], v[2:3] op_sel_hi:[1,0]
	v_pk_mul_f32 v[64:65], v[64:65], v[2:3] op_sel_hi:[1,0]
	v_pk_mul_f32 v[62:63], v[62:63], v[2:3] op_sel_hi:[1,0]
	v_pk_mul_f32 v[60:61], v[60:61], v[2:3] op_sel_hi:[1,0]
	v_pk_mul_f32 v[58:59], v[58:59], v[2:3] op_sel_hi:[1,0]
	v_pk_mul_f32 v[56:57], v[56:57], v[2:3] op_sel_hi:[1,0]
	v_pk_mul_f32 v[54:55], v[54:55], v[2:3] op_sel_hi:[1,0]
	v_pk_mul_f32 v[52:53], v[52:53], v[2:3] op_sel_hi:[1,0]
	v_pk_mul_f32 v[50:51], v[50:51], v[2:3] op_sel_hi:[1,0]
	v_pk_mul_f32 v[48:49], v[48:49], v[2:3] op_sel_hi:[1,0]
	v_pk_mul_f32 v[46:47], v[46:47], v[2:3] op_sel_hi:[1,0]
	v_pk_mul_f32 v[44:45], v[44:45], v[2:3] op_sel_hi:[1,0]
	v_pk_mul_f32 v[42:43], v[42:43], v[2:3] op_sel_hi:[1,0]
	v_pk_mul_f32 v[40:41], v[40:41], v[2:3] op_sel_hi:[1,0]
	v_pk_mul_f32 v[38:39], v[38:39], v[2:3] op_sel_hi:[1,0]
	v_pk_mul_f32 v[36:37], v[36:37], v[2:3] op_sel_hi:[1,0]
	v_pk_mul_f32 v[34:35], v[34:35], v[2:3] op_sel_hi:[1,0]
	v_pk_mul_f32 v[32:33], v[32:33], v[2:3] op_sel_hi:[1,0]
	v_pk_mul_f32 v[30:31], v[30:31], v[2:3] op_sel_hi:[1,0]
	v_pk_mul_f32 v[28:29], v[28:29], v[2:3] op_sel_hi:[1,0]
	v_pk_mul_f32 v[26:27], v[26:27], v[2:3] op_sel_hi:[1,0]
	v_pk_mul_f32 v[24:25], v[24:25], v[2:3] op_sel_hi:[1,0]
	v_pk_mul_f32 v[22:23], v[22:23], v[2:3] op_sel_hi:[1,0]
	v_pk_mul_f32 v[20:21], v[20:21], v[2:3] op_sel_hi:[1,0]
	v_pk_mul_f32 v[18:19], v[18:19], v[2:3] op_sel_hi:[1,0]

; template <int MODE, int DK, bool PASS2> ...
;     ...
;                     for (int r = 0; r < 16; ++r) { s0[r] *= sl2; s1[r] *= sl2; }
;                     if (need_bias || need_causal || need_win) {
; #pragma unroll
;                         for (int i = 0; i < 32; ++i) {
;                             const int s = kv0 + (i >> 3) * 16 + 8 * g + (i & 7);
;                             const int dist = t_lane - ((MODE == M_CMP) ? 16 * s + 31 : s);
;                             float v = (i < 16) ? s0[i & 15] : s1[i & 15];
;                             if (need_bias) { const int di = dist < 0 ? 0 : (dist > 128 ? 128 : dist); v += tb[di]; }
;                             bool msk = dist < 0;
;                             if (MODE == M_WIN) msk = msk || dist >= 512;
;                             if (msk) v = NEG;
;                             if (i < 16) s0[i & 15] = v; else s1[i & 15] = v;
.LBB0_2135:
	s_andn2_saveexec_b64 s[6:7], s[6:7]
	s_cbranch_execz .LBB0_2141
	s_setprio 1
	v_pk_mul_f32 v[162:163], v[82:83], s[12:13] op_sel_hi:[1,0]
	v_pk_mul_f32 v[98:99], v[98:99], s[12:13] op_sel_hi:[1,0]
	v_pk_mul_f32 v[160:161], v[84:85], s[12:13] op_sel_hi:[1,0]
	v_pk_mul_f32 v[100:101], v[100:101], s[12:13] op_sel_hi:[1,0]
	v_pk_mul_f32 v[4:5], v[86:87], s[12:13] op_sel_hi:[1,0]
	v_pk_mul_f32 v[6:7], v[102:103], s[12:13] op_sel_hi:[1,0]
	v_pk_mul_f32 v[8:9], v[88:89], s[12:13] op_sel_hi:[1,0]
	v_pk_mul_f32 v[10:11], v[104:105], s[12:13] op_sel_hi:[1,0]
	v_pk_mul_f32 v[12:13], v[90:91], s[12:13] op_sel_hi:[1,0]
	v_pk_mul_f32 v[14:15], v[106:107], s[12:13] op_sel_hi:[1,0]
	v_pk_mul_f32 v[16:17], v[92:93], s[12:13] op_sel_hi:[1,0]
	v_pk_mul_f32 v[82:83], v[108:109], s[12:13] op_sel_hi:[1,0]
	v_pk_mul_f32 v[84:85], v[94:95], s[12:13] op_sel_hi:[1,0]
	v_pk_mul_f32 v[86:87], v[110:111], s[12:13] op_sel_hi:[1,0]
	v_pk_mul_f32 v[88:89], v[96:97], s[12:13] op_sel_hi:[1,0]
	v_pk_mul_f32 v[90:91], v[112:113], s[12:13] op_sel_hi:[1,0]
	s_and_saveexec_b64 s[28:29], s[4:5]
	s_cbranch_execz .LBB0_2138
	v_add_u32_e32 v112, s8, v199
	v_add_u32_e32 v113, v112, v1
	v_add_u32_e32 v164, v112, v158
	v_add_u32_e32 v165, v112, v149
	v_add_u32_e32 v166, v112, v148
	v_add_u32_e32 v167, v112, v151
	v_add_u32_e32 v168, v112, v150
	v_add_u32_e32 v169, v112, v153
	v_add_u32_e32 v170, v112, v152
	v_med3_i32 v92, v164, 0, v190
	v_med3_i32 v93, v113, 0, v190
	v_med3_i32 v94, v166, 0, v190
	v_med3_i32 v95, v165, 0, v190
	v_med3_i32 v96, v168, 0, v190
	v_med3_i32 v97, v167, 0, v190
	v_med3_i32 v102, v170, 0, v190
	v_med3_i32 v103, v169, 0, v190
	v_lshl_add_u32 v92, v92, 2, s53
	v_lshl_add_u32 v93, v93, 2, s53
	v_lshl_add_u32 v94, v94, 2, s53
	v_lshl_add_u32 v95, v95, 2, s53
	v_lshl_add_u32 v96, v96, 2, s53
	v_lshl_add_u32 v97, v97, 2, s53
	v_lshl_add_u32 v102, v102, 2, s53
	v_lshl_add_u32 v103, v103, 2, s53
	ds_read_b32 v92, v92
	ds_read_b32 v93, v93
	ds_read_b32 v94, v94
	ds_read_b32 v95, v95
	ds_read_b32 v96, v96
	ds_read_b32 v97, v97
	ds_read_b32 v102, v102
	ds_read_b32 v103, v103
	s_waitcnt lgkmcnt(6)
	v_pk_add_f32 v[92:93], v[162:163], v[92:93]
	v_cmp_lt_i32_e32 vcc, -1, v164
	s_waitcnt lgkmcnt(4)
	v_pk_add_f32 v[94:95], v[160:161], v[94:95]
	v_add_u32_e32 v104, -16, v112
	v_cndmask_b32_e32 v162, v191, v92, vcc
	v_cmp_lt_i32_e32 vcc, -1, v113
	s_waitcnt lgkmcnt(2)
	v_pk_add_f32 v[4:5], v[4:5], v[96:97]
	v_add_u32_e32 v171, v104, v1
	v_cndmask_b32_e32 v163, v191, v93, vcc
	v_cmp_lt_i32_e32 vcc, -1, v166
	v_add_u32_e32 v172, v104, v158
	v_add_u32_e32 v173, v104, v149
	v_cndmask_b32_e32 v160, v191, v94, vcc
	v_cmp_lt_i32_e32 vcc, -1, v165
	v_add_u32_e32 v174, v104, v148
	v_add_u32_e32 v175, v104, v151
	v_cndmask_b32_e32 v161, v191, v95, vcc
	v_cmp_lt_i32_e32 vcc, -1, v168
	v_add_u32_e32 v176, v104, v150
	v_add_u32_e32 v207, v104, v152
	v_cndmask_b32_e32 v4, v191, v4, vcc
	v_cmp_lt_i32_e32 vcc, -1, v167
	v_med3_i32 v105, v172, 0, v190
	v_med3_i32 v106, v171, 0, v190
	v_med3_i32 v107, v174, 0, v190
	v_med3_i32 v108, v173, 0, v190
	v_med3_i32 v109, v176, 0, v190
	v_med3_i32 v110, v175, 0, v190
	v_add_u32_e32 v177, v104, v153
	v_med3_i32 v104, v207, 0, v190
	s_waitcnt lgkmcnt(0)
	v_pk_add_f32 v[8:9], v[8:9], v[102:103]
	v_cndmask_b32_e32 v5, v191, v5, vcc
	v_cmp_lt_i32_e32 vcc, -1, v170
	v_lshl_add_u32 v105, v105, 2, s53
	v_lshl_add_u32 v106, v106, 2, s53
	v_lshl_add_u32 v107, v107, 2, s53
	v_lshl_add_u32 v108, v108, 2, s53
	v_lshl_add_u32 v109, v109, 2, s53
	v_lshl_add_u32 v110, v110, 2, s53
	v_lshl_add_u32 v111, v104, 2, s53
	v_med3_i32 v104, v177, 0, v190
	v_cndmask_b32_e32 v8, v191, v8, vcc
	v_cmp_lt_i32_e32 vcc, -1, v169
	v_lshl_add_u32 v209, v104, 2, s53
	ds_read_b32 v104, v105
	ds_read_b32 v105, v106
	ds_read_b32 v106, v107
	ds_read_b32 v107, v108
	ds_read_b32 v108, v109
	ds_read_b32 v109, v110
	ds_read_b32 v110, v111
	ds_read_b32 v111, v209
	s_waitcnt lgkmcnt(6)
	v_pk_add_f32 v[12:13], v[12:13], v[104:105]
	v_cndmask_b32_e32 v9, v191, v9, vcc
	v_cmp_lt_i32_e32 vcc, -1, v172
	s_waitcnt lgkmcnt(4)
	v_pk_add_f32 v[16:17], v[16:17], v[106:107]
	s_waitcnt lgkmcnt(2)
	v_pk_add_f32 v[84:85], v[84:85], v[108:109]
	v_cndmask_b32_e32 v12, v191, v12, vcc
	v_cmp_lt_i32_e32 vcc, -1, v171
	s_waitcnt lgkmcnt(0)
; template <int MODE, int DK, bool PASS2> ...
;     ...
;                         for (int i = 0; i < 32; ++i) {
;                             const int s = kv0 + (i >> 3) * 16 + 8 * g + (i & 7);
;                             const int dist = t_lane - ((MODE == M_CMP) ? 16 * s + 31 : s);
;                             float v = (i < 16) ? s0[i & 15] : s1[i & 15];
;                             if (need_bias) { const int di = dist < 0 ? 0 : (dist > 128 ? 128 : dist); v += tb[di]; }
;                             bool msk = dist < 0;
;                             if (MODE == M_WIN) msk = msk || dist >= 512;
;                             if (msk) v = NEG;
;                             if (i < 16) s0[i & 15] = v; else s1[i & 15] = v;
	v_pk_add_f32 v[88:89], v[88:89], v[110:111]
	v_cndmask_b32_e32 v13, v191, v13, vcc
	v_cmp_lt_i32_e32 vcc, -1, v174
	s_nop 1
	v_cndmask_b32_e32 v16, v191, v16, vcc
	v_cmp_lt_i32_e32 vcc, -1, v173
	s_nop 1
	v_cndmask_b32_e32 v17, v191, v17, vcc
	v_cmp_lt_i32_e32 vcc, -1, v176
	s_nop 1
	v_cndmask_b32_e32 v84, v191, v84, vcc
	v_cmp_lt_i32_e32 vcc, -1, v175
	s_nop 1
	v_cndmask_b32_e32 v85, v191, v85, vcc
	v_cmp_lt_i32_e32 vcc, -1, v207
	s_nop 1
	v_cndmask_b32_e32 v88, v191, v88, vcc
	v_cmp_lt_i32_e32 vcc, -1, v177
	s_nop 1
	v_cndmask_b32_e32 v89, v191, v89, vcc
	v_subrev_u32_e32 v92, 32, v112
	v_add_u32_e32 v113, v92, v1
	v_add_u32_e32 v164, v92, v158
	v_add_u32_e32 v165, v92, v149
	v_add_u32_e32 v166, v92, v148
	v_add_u32_e32 v167, v92, v151
	v_add_u32_e32 v168, v92, v150
	v_add_u32_e32 v170, v92, v152
	v_med3_i32 v93, v164, 0, v190
	v_med3_i32 v94, v113, 0, v190
	v_med3_i32 v95, v166, 0, v190
	v_med3_i32 v96, v165, 0, v190
	v_med3_i32 v97, v168, 0, v190
	v_med3_i32 v102, v167, 0, v190
	v_add_u32_e32 v169, v92, v153
	v_med3_i32 v92, v170, 0, v190
	v_lshl_add_u32 v93, v93, 2, s53
	v_lshl_add_u32 v94, v94, 2, s53
	v_lshl_add_u32 v95, v95, 2, s53
	v_lshl_add_u32 v96, v96, 2, s53
	v_lshl_add_u32 v97, v97, 2, s53
	v_lshl_add_u32 v102, v102, 2, s53
	v_lshl_add_u32 v103, v92, 2, s53
	v_med3_i32 v92, v169, 0, v190
	v_lshl_add_u32 v104, v92, 2, s53
	ds_read_b32 v92, v93
	ds_read_b32 v93, v94
	ds_read_b32 v94, v95
	ds_read_b32 v95, v96
	ds_read_b32 v96, v97
	ds_read_b32 v97, v102
	ds_read_b32 v102, v103
	ds_read_b32 v103, v104
	s_waitcnt lgkmcnt(6)
	v_pk_add_f32 v[92:93], v[98:99], v[92:93]
	v_cmp_lt_i32_e32 vcc, -1, v164
	s_waitcnt lgkmcnt(4)
	v_pk_add_f32 v[94:95], v[100:101], v[94:95]
	v_subrev_u32_e32 v104, 48, v112
	v_cndmask_b32_e32 v98, v191, v92, vcc
	v_cmp_lt_i32_e32 vcc, -1, v113
	s_waitcnt lgkmcnt(2)
	v_pk_add_f32 v[6:7], v[6:7], v[96:97]
	v_add_u32_e32 v112, v104, v1
	v_cndmask_b32_e32 v99, v191, v93, vcc
	v_cmp_lt_i32_e32 vcc, -1, v166
	v_add_u32_e32 v171, v104, v158
	v_add_u32_e32 v172, v104, v149
	v_cndmask_b32_e32 v100, v191, v94, vcc
	v_cmp_lt_i32_e32 vcc, -1, v165
	v_add_u32_e32 v173, v104, v148
	v_add_u32_e32 v174, v104, v151
	v_cndmask_b32_e32 v101, v191, v95, vcc
	v_cmp_lt_i32_e32 vcc, -1, v168
	v_add_u32_e32 v175, v104, v150
	v_add_u32_e32 v177, v104, v152
	v_cndmask_b32_e32 v6, v191, v6, vcc
	v_cmp_lt_i32_e32 vcc, -1, v167
	v_med3_i32 v105, v171, 0, v190
	v_med3_i32 v106, v112, 0, v190
	v_med3_i32 v107, v173, 0, v190
	v_med3_i32 v108, v172, 0, v190
	v_med3_i32 v109, v175, 0, v190
	v_med3_i32 v110, v174, 0, v190
	v_add_u32_e32 v176, v104, v153
	v_med3_i32 v104, v177, 0, v190
	s_waitcnt lgkmcnt(0)
	v_pk_add_f32 v[10:11], v[10:11], v[102:103]
	v_cndmask_b32_e32 v7, v191, v7, vcc
	v_cmp_lt_i32_e32 vcc, -1, v170
	v_lshl_add_u32 v105, v105, 2, s53
	v_lshl_add_u32 v106, v106, 2, s53
	v_lshl_add_u32 v107, v107, 2, s53
	v_lshl_add_u32 v108, v108, 2, s53
	v_lshl_add_u32 v109, v109, 2, s53
	v_lshl_add_u32 v110, v110, 2, s53
	v_lshl_add_u32 v111, v104, 2, s53
	v_med3_i32 v104, v176, 0, v190
	v_cndmask_b32_e32 v10, v191, v10, vcc
	v_cmp_lt_i32_e32 vcc, -1, v169
	v_lshl_add_u32 v207, v104, 2, s53
	ds_read_b32 v104, v105
	ds_read_b32 v105, v106
	ds_read_b32 v106, v107
	ds_read_b32 v107, v108
	ds_read_b32 v108, v109
	ds_read_b32 v109, v110
	ds_read_b32 v110, v111
	ds_read_b32 v111, v207
	s_waitcnt lgkmcnt(6)
	v_pk_add_f32 v[14:15], v[14:15], v[104:105]
	v_cndmask_b32_e32 v11, v191, v11, vcc
	v_cmp_lt_i32_e32 vcc, -1, v171
	s_waitcnt lgkmcnt(4)
	v_pk_add_f32 v[82:83], v[82:83], v[106:107]
	s_waitcnt lgkmcnt(2)
	v_pk_add_f32 v[86:87], v[86:87], v[108:109]
	v_cndmask_b32_e32 v14, v191, v14, vcc
	v_cmp_lt_i32_e32 vcc, -1, v112
	s_waitcnt lgkmcnt(0)
	v_pk_add_f32 v[90:91], v[90:91], v[110:111]
	v_cndmask_b32_e32 v15, v191, v15, vcc
	v_cmp_lt_i32_e32 vcc, -1, v173
	s_nop 1
	v_cndmask_b32_e32 v82, v191, v82, vcc
	v_cmp_lt_i32_e32 vcc, -1, v172
	s_nop 1
	v_cndmask_b32_e32 v83, v191, v83, vcc
	v_cmp_lt_i32_e32 vcc, -1, v175
	s_nop 1
	v_cndmask_b32_e32 v86, v191, v86, vcc
	v_cmp_lt_i32_e32 vcc, -1, v174
	s_nop 1
	v_cndmask_b32_e32 v87, v191, v87, vcc
	v_cmp_lt_i32_e32 vcc, -1, v177
	s_nop 1
	v_cndmask_b32_e32 v90, v191, v90, vcc
	v_cmp_lt_i32_e32 vcc, -1, v176
	s_nop 1
	v_cndmask_b32_e32 v91, v191, v91, vcc

; template <int MODE, int DK, bool PASS2> ...
;     ...
;                     for (int r = 0; r < 16; ++r) { s0[r] *= sl2; s1[r] *= sl2; }
;                     if (need_bias || need_causal || need_win) {
; #pragma unroll
;                         for (int i = 0; i < 32; ++i) {
;                             const int s = kv0 + (i >> 3) * 16 + 8 * g + (i & 7);
;                             const int dist = t_lane - ((MODE == M_CMP) ? 16 * s + 31 : s);
;                             float v = (i < 16) ? s0[i & 15] : s1[i & 15];
;                             if (need_bias) { const int di = dist < 0 ? 0 : (dist > 128 ? 128 : dist); v += tb[di]; }
;                             bool msk = dist < 0;
;                             if (MODE == M_WIN) msk = msk || dist >= 512;
;                             if (msk) v = NEG;
;                             if (i < 16) s0[i & 15] = v; else s1[i & 15] = v;
.LBB0_2169:
	s_andn2_saveexec_b64 s[70:71], s[8:9]
	s_cbranch_execz .LBB0_2239
	s_setprio 1
	v_pk_mul_f32 v[170:171], v[98:99], s[58:59] op_sel_hi:[1,0]
	v_pk_mul_f32 v[168:169], v[82:83], s[58:59] op_sel_hi:[1,0]
	v_pk_mul_f32 v[100:101], v[100:101], s[58:59] op_sel_hi:[1,0]
	v_pk_mul_f32 v[166:167], v[84:85], s[58:59] op_sel_hi:[1,0]
	v_pk_mul_f32 v[98:99], v[102:103], s[58:59] op_sel_hi:[1,0]
	v_pk_mul_f32 v[86:87], v[86:87], s[58:59] op_sel_hi:[1,0]
	v_pk_mul_f32 v[82:83], v[104:105], s[58:59] op_sel_hi:[1,0]
	v_pk_mul_f32 v[84:85], v[88:89], s[58:59] op_sel_hi:[1,0]
	v_pk_mul_f32 v[14:15], v[106:107], s[58:59] op_sel_hi:[1,0]
	v_pk_mul_f32 v[16:17], v[90:91], s[58:59] op_sel_hi:[1,0]
	v_pk_mul_f32 v[10:11], v[108:109], s[58:59] op_sel_hi:[1,0]
	v_pk_mul_f32 v[12:13], v[92:93], s[58:59] op_sel_hi:[1,0]
	v_pk_mul_f32 v[6:7], v[110:111], s[58:59] op_sel_hi:[1,0]
	v_pk_mul_f32 v[8:9], v[94:95], s[58:59] op_sel_hi:[1,0]
	v_pk_mul_f32 v[4:5], v[112:113], s[58:59] op_sel_hi:[1,0]
	v_pk_mul_f32 v[88:89], v[96:97], s[58:59] op_sel_hi:[1,0]
	s_or_b64 s[6:7], s[4:5], s[6:7]
	s_and_saveexec_b64 s[72:73], s[6:7]
	s_cbranch_execz .LBB0_2236
	v_add_u32_e32 v90, v196, v201
	v_subrev_u32_e32 v91, 31, v90
	s_and_saveexec_b64 s[6:7], s[4:5]
	s_cbranch_execz .LBB0_2179
	v_med3_i32 v92, v91, 0, v187
	v_lshl_add_u32 v92, v92, 2, v186
	v_add_u32_e32 v92, 0x11a00, v92
	ds_read_b32 v92, v92
	s_waitcnt lgkmcnt(0)
	v_add_f32_e32 v170, v170, v92
	s_or_b64 exec, exec, s[6:7]
	v_subrev_u32_e32 v92, 32, v90
	s_and_saveexec_b64 s[6:7], s[4:5]
	s_cbranch_execnz .LBB0_2180

; template <int MODE, int DK, bool PASS2> ...
;     ...
;                     for (int r = 0; r < 16; ++r) { s0[r] *= sl2; s1[r] *= sl2; }
;                     if (need_bias || need_causal || need_win) {
; #pragma unroll
;                         for (int i = 0; i < 32; ++i) {
;                             const int s = kv0 + (i >> 3) * 16 + 8 * g + (i & 7);
;                             const int dist = t_lane - ((MODE == M_CMP) ? 16 * s + 31 : s);
;                             float v = (i < 16) ? s0[i & 15] : s1[i & 15];
;                             if (need_bias) { const int di = dist < 0 ? 0 : (dist > 128 ? 128 : dist); v += tb[di]; }
;                             bool msk = dist < 0;
;                             if (MODE == M_WIN) msk = msk || dist >= 512;
;                             if (msk) v = NEG;
;                             if (i < 16) s0[i & 15] = v; else s1[i & 15] = v;
.LBB0_2273:
	s_andn2_saveexec_b64 s[6:7], s[6:7]
	s_cbranch_execz .LBB0_2279
	s_setprio 1
	v_pk_mul_f32 v[200:201], v[82:83], s[34:35] op_sel_hi:[1,0]
	v_pk_mul_f32 v[98:99], v[98:99], s[34:35] op_sel_hi:[1,0]
	v_pk_mul_f32 v[16:17], v[84:85], s[34:35] op_sel_hi:[1,0]
	v_pk_mul_f32 v[100:101], v[100:101], s[34:35] op_sel_hi:[1,0]
	v_pk_mul_f32 v[14:15], v[86:87], s[34:35] op_sel_hi:[1,0]
	v_pk_mul_f32 v[82:83], v[102:103], s[34:35] op_sel_hi:[1,0]
	v_pk_mul_f32 v[12:13], v[88:89], s[34:35] op_sel_hi:[1,0]
	v_pk_mul_f32 v[84:85], v[104:105], s[34:35] op_sel_hi:[1,0]
	v_pk_mul_f32 v[10:11], v[90:91], s[34:35] op_sel_hi:[1,0]
	v_pk_mul_f32 v[86:87], v[106:107], s[34:35] op_sel_hi:[1,0]
	v_pk_mul_f32 v[8:9], v[92:93], s[34:35] op_sel_hi:[1,0]
	v_pk_mul_f32 v[88:89], v[108:109], s[34:35] op_sel_hi:[1,0]
	v_pk_mul_f32 v[6:7], v[94:95], s[34:35] op_sel_hi:[1,0]
	v_pk_mul_f32 v[90:91], v[110:111], s[34:35] op_sel_hi:[1,0]
	v_pk_mul_f32 v[4:5], v[96:97], s[34:35] op_sel_hi:[1,0]
	v_pk_mul_f32 v[92:93], v[112:113], s[34:35] op_sel_hi:[1,0]
	s_and_saveexec_b64 s[18:19], s[4:5]
	s_cbranch_execz .LBB0_2276
	v_add_u32_e32 v94, v241, v242
	v_subrev_u32_e32 v96, s30, v170
	v_subrev_u32_e32 v97, s30, v163
	v_subrev_u32_e32 v102, s30, v172
	v_subrev_u32_e32 v103, s30, v165
	v_subrev_u32_e32 v110, s30, v174
	v_add_u32_e32 v104, 0x3f0, v94
	v_add_u32_e32 v105, 0x3e0, v94
	v_lshl_add_u32 v106, v97, 4, v1
	v_lshl_add_u32 v107, v96, 4, v166
	v_lshl_add_u32 v108, v103, 4, v1
	v_lshl_add_u32 v109, v102, 4, v166
	v_subrev_u32_e32 v111, s30, v167
	v_lshl_add_u32 v110, v110, 4, v166
	v_med3_i32 v95, v104, 0, v219
	v_med3_i32 v94, v105, 0, v219
	v_med3_i32 v96, v107, 0, v219
	v_med3_i32 v97, v106, 0, v219
	v_med3_i32 v102, v109, 0, v219
	v_med3_i32 v103, v108, 0, v219
	v_lshl_add_u32 v111, v111, 4, v1
	v_med3_i32 v112, v110, 0, v219
	v_lshl_add_u32 v95, v95, 2, v229
	v_lshl_add_u32 v94, v94, 2, v229
	v_lshl_add_u32 v96, v96, 2, v229
	v_lshl_add_u32 v97, v97, 2, v229
	v_lshl_add_u32 v102, v102, 2, v229
	v_lshl_add_u32 v103, v103, 2, v229
	v_lshl_add_u32 v112, v112, 2, v229
	v_med3_i32 v113, v111, 0, v219
	v_lshl_add_u32 v113, v113, 2, v229
	ds_read_b32 v202, v95
	ds_read_b32 v203, v94
	ds_read_b32 v94, v96
	ds_read_b32 v95, v97
	ds_read_b32 v96, v102
	ds_read_b32 v97, v103
	ds_read_b32 v102, v112
	ds_read_b32 v103, v113
	s_waitcnt lgkmcnt(7)
	v_add_f32_e32 v112, v200, v202
	v_cmp_lt_i32_e32 vcc, -1, v104
	s_waitcnt lgkmcnt(6)
	v_add_f32_e32 v104, v201, v203
	s_waitcnt lgkmcnt(4)
	v_pk_add_f32 v[16:17], v[16:17], v[94:95]
	v_cndmask_b32_e32 v200, v220, v112, vcc
	v_cmp_lt_i32_e32 vcc, -1, v105
	s_waitcnt lgkmcnt(2)
	v_pk_add_f32 v[14:15], v[14:15], v[96:97]
	s_waitcnt lgkmcnt(0)
	v_pk_add_f32 v[12:13], v[12:13], v[102:103]
	v_cndmask_b32_e32 v201, v220, v104, vcc
	v_cmp_lt_i32_e32 vcc, -1, v107
	s_nop 1
	v_cndmask_b32_e32 v16, v220, v16, vcc
	v_cmp_lt_i32_e32 vcc, -1, v106
	s_nop 1
	v_cndmask_b32_e32 v17, v220, v17, vcc
	v_cmp_lt_i32_e32 vcc, -1, v109
	s_nop 1
	v_cndmask_b32_e32 v14, v220, v14, vcc
	v_cmp_lt_i32_e32 vcc, -1, v108
	s_nop 1
	v_cndmask_b32_e32 v15, v220, v15, vcc
	v_cmp_lt_i32_e32 vcc, -1, v110
	s_nop 1
	v_cndmask_b32_e32 v12, v220, v12, vcc
	v_cmp_lt_i32_e32 vcc, -1, v111
	s_nop 1
	v_cndmask_b32_e32 v13, v220, v13, vcc
	v_subrev_u32_e32 v94, s30, v176
	v_subrev_u32_e32 v95, s30, v171
	v_subrev_u32_e32 v96, s30, v178
	v_subrev_u32_e32 v97, s30, v173
	v_subrev_u32_e32 v102, s30, v180
	v_subrev_u32_e32 v103, s30, v175
	v_subrev_u32_e32 v104, s30, v182
	v_subrev_u32_e32 v105, s30, v177
	v_lshl_add_u32 v106, v95, 4, v1
	v_lshl_add_u32 v107, v94, 4, v166
	v_lshl_add_u32 v108, v97, 4, v1
	v_lshl_add_u32 v109, v96, 4, v166
	v_lshl_add_u32 v110, v103, 4, v1
	v_lshl_add_u32 v111, v102, 4, v166
	v_lshl_add_u32 v112, v105, 4, v1
	v_lshl_add_u32 v113, v104, 4, v166
	v_med3_i32 v94, v107, 0, v219
	v_med3_i32 v95, v106, 0, v219
	v_med3_i32 v96, v109, 0, v219
	v_med3_i32 v97, v108, 0, v219
	v_med3_i32 v102, v111, 0, v219
	v_med3_i32 v103, v110, 0, v219
	v_med3_i32 v104, v113, 0, v219
	v_med3_i32 v105, v112, 0, v219
	v_lshl_add_u32 v94, v94, 2, v229
	v_lshl_add_u32 v95, v95, 2, v229
	v_lshl_add_u32 v96, v96, 2, v229
	v_lshl_add_u32 v97, v97, 2, v229
	v_lshl_add_u32 v102, v102, 2, v229
	v_lshl_add_u32 v103, v103, 2, v229
	v_lshl_add_u32 v104, v104, 2, v229
	v_lshl_add_u32 v105, v105, 2, v229
	ds_read_b32 v94, v94
	ds_read_b32 v95, v95
	ds_read_b32 v96, v96
	ds_read_b32 v97, v97
	ds_read_b32 v102, v102
	ds_read_b32 v103, v103
	ds_read_b32 v104, v104
	ds_read_b32 v105, v105
	s_waitcnt lgkmcnt(6)
	v_pk_add_f32 v[10:11], v[10:11], v[94:95]
	v_cmp_lt_i32_e32 vcc, -1, v107
	s_waitcnt lgkmcnt(4)
	v_pk_add_f32 v[8:9], v[8:9], v[96:97]
	s_waitcnt lgkmcnt(2)
	v_pk_add_f32 v[6:7], v[6:7], v[102:103]
	v_cndmask_b32_e32 v10, v220, v10, vcc
	v_cmp_lt_i32_e32 vcc, -1, v106
	s_waitcnt lgkmcnt(0)
; template <int MODE, int DK, bool PASS2> ...
;     ...
;                     if (need_bias || need_causal || need_win) {
; #pragma unroll
;                         for (int i = 0; i < 32; ++i) {
;                             const int s = kv0 + (i >> 3) * 16 + 8 * g + (i & 7);
;                             const int dist = t_lane - ((MODE == M_CMP) ? 16 * s + 31 : s);
;                             float v = (i < 16) ? s0[i & 15] : s1[i & 15];
;                             if (need_bias) { const int di = dist < 0 ? 0 : (dist > 128 ? 128 : dist); v += tb[di]; }
;                             bool msk = dist < 0;
;                             if (MODE == M_WIN) msk = msk || dist >= 512;
;                             if (msk) v = NEG;
;                             if (i < 16) s0[i & 15] = v; else s1[i & 15] = v;
;                             if ((i & 7) == 7) __builtin_amdgcn_sched_barrier(0);
;                         }
;                     }
	v_pk_add_f32 v[4:5], v[4:5], v[104:105]
	v_cndmask_b32_e32 v11, v220, v11, vcc
	v_cmp_lt_i32_e32 vcc, -1, v109
	s_nop 1
	v_cndmask_b32_e32 v8, v220, v8, vcc
	v_cmp_lt_i32_e32 vcc, -1, v108
	s_nop 1
	v_cndmask_b32_e32 v9, v220, v9, vcc
	v_cmp_lt_i32_e32 vcc, -1, v111
	s_nop 1
	v_cndmask_b32_e32 v6, v220, v6, vcc
	v_cmp_lt_i32_e32 vcc, -1, v110
	s_nop 1
	v_cndmask_b32_e32 v7, v220, v7, vcc
	v_cmp_lt_i32_e32 vcc, -1, v113
	s_nop 1
	v_cndmask_b32_e32 v4, v220, v4, vcc
	v_cmp_lt_i32_e32 vcc, -1, v112
	s_nop 1
	v_cndmask_b32_e32 v5, v220, v5, vcc
	v_subrev_u32_e32 v94, s30, v184
	v_subrev_u32_e32 v95, s30, v179
	v_subrev_u32_e32 v96, s30, v186
	v_subrev_u32_e32 v97, s30, v181
	v_subrev_u32_e32 v102, s30, v188
	v_subrev_u32_e32 v103, s30, v183
	v_subrev_u32_e32 v104, s30, v190
	v_subrev_u32_e32 v105, s30, v185
	v_lshl_add_u32 v202, v95, 4, v1
	v_lshl_add_u32 v203, v94, 4, v166
	v_lshl_add_u32 v204, v97, 4, v1
	v_lshl_add_u32 v205, v96, 4, v166
	v_lshl_add_u32 v206, v103, 4, v1
	v_lshl_add_u32 v207, v102, 4, v166
	v_lshl_add_u32 v208, v105, 4, v1
	v_lshl_add_u32 v209, v104, 4, v166
	v_med3_i32 v94, v203, 0, v219
	v_med3_i32 v95, v202, 0, v219
	v_med3_i32 v96, v205, 0, v219
	v_med3_i32 v97, v204, 0, v219
	v_med3_i32 v102, v207, 0, v219
	v_med3_i32 v103, v206, 0, v219
	v_med3_i32 v104, v209, 0, v219
	v_med3_i32 v105, v208, 0, v219
	v_lshl_add_u32 v94, v94, 2, v229
	v_lshl_add_u32 v95, v95, 2, v229
	v_lshl_add_u32 v96, v96, 2, v229
	v_lshl_add_u32 v97, v97, 2, v229
	v_lshl_add_u32 v102, v102, 2, v229
	v_lshl_add_u32 v103, v103, 2, v229
	v_lshl_add_u32 v104, v104, 2, v229
	v_lshl_add_u32 v105, v105, 2, v229
	ds_read_b32 v94, v94
	ds_read_b32 v95, v95
	ds_read_b32 v96, v96
	ds_read_b32 v97, v97
	ds_read_b32 v102, v102
	ds_read_b32 v103, v103
	ds_read_b32 v104, v104
	ds_read_b32 v105, v105
	s_waitcnt lgkmcnt(6)
	v_pk_add_f32 v[94:95], v[98:99], v[94:95]
	v_cmp_lt_i32_e32 vcc, -1, v203
	s_waitcnt lgkmcnt(4)
	v_pk_add_f32 v[96:97], v[100:101], v[96:97]
	v_subrev_u32_e32 v106, s30, v192
	v_cndmask_b32_e32 v98, v220, v94, vcc
	v_cmp_lt_i32_e32 vcc, -1, v202
	v_subrev_u32_e32 v107, s30, v187
	v_subrev_u32_e32 v108, s30, v194
	v_cndmask_b32_e32 v99, v220, v95, vcc
	v_cmp_lt_i32_e32 vcc, -1, v205
	v_subrev_u32_e32 v109, s30, v189
	v_subrev_u32_e32 v110, s30, v196
	v_cndmask_b32_e32 v100, v220, v96, vcc
	v_cmp_lt_i32_e32 vcc, -1, v204
	v_subrev_u32_e32 v111, s30, v191
	v_subrev_u32_e32 v112, s30, v198
	v_subrev_u32_e32 v113, s30, v193
	s_waitcnt lgkmcnt(2)
	v_pk_add_f32 v[82:83], v[82:83], v[102:103]
	v_cndmask_b32_e32 v101, v220, v97, vcc
	v_cmp_lt_i32_e32 vcc, -1, v207
	v_lshl_add_u32 v210, v107, 4, v1
	v_lshl_add_u32 v211, v106, 4, v166
	v_lshl_add_u32 v212, v109, 4, v1
	v_lshl_add_u32 v213, v108, 4, v166
	v_lshl_add_u32 v214, v111, 4, v1
	v_lshl_add_u32 v215, v110, 4, v166
	v_lshl_add_u32 v216, v113, 4, v1
	v_lshl_add_u32 v217, v112, 4, v166
	v_cndmask_b32_e32 v82, v220, v82, vcc
	v_cmp_lt_i32_e32 vcc, -1, v206
	v_med3_i32 v106, v211, 0, v219
	v_med3_i32 v107, v210, 0, v219
	v_med3_i32 v108, v213, 0, v219
	v_med3_i32 v109, v212, 0, v219
	v_med3_i32 v110, v215, 0, v219
	v_med3_i32 v111, v214, 0, v219
	v_med3_i32 v112, v217, 0, v219
	v_med3_i32 v113, v216, 0, v219
	s_waitcnt lgkmcnt(0)
	v_pk_add_f32 v[84:85], v[84:85], v[104:105]
	v_cndmask_b32_e32 v83, v220, v83, vcc
	v_cmp_lt_i32_e32 vcc, -1, v209
	v_lshl_add_u32 v106, v106, 2, v229
	v_lshl_add_u32 v107, v107, 2, v229
	v_lshl_add_u32 v108, v108, 2, v229
	v_lshl_add_u32 v109, v109, 2, v229
	v_lshl_add_u32 v110, v110, 2, v229
	v_lshl_add_u32 v111, v111, 2, v229
	v_lshl_add_u32 v112, v112, 2, v229
	v_lshl_add_u32 v113, v113, 2, v229
	v_cndmask_b32_e32 v84, v220, v84, vcc
	v_cmp_lt_i32_e32 vcc, -1, v208
	ds_read_b32 v106, v106
	ds_read_b32 v107, v107
	ds_read_b32 v108, v108
	ds_read_b32 v109, v109
	ds_read_b32 v110, v110
	ds_read_b32 v111, v111
	ds_read_b32 v112, v112
	ds_read_b32 v113, v113
	s_waitcnt lgkmcnt(6)
	v_pk_add_f32 v[86:87], v[86:87], v[106:107]
	v_cndmask_b32_e32 v85, v220, v85, vcc
	v_cmp_lt_i32_e32 vcc, -1, v211
	s_waitcnt lgkmcnt(4)
	v_pk_add_f32 v[88:89], v[88:89], v[108:109]
	s_waitcnt lgkmcnt(2)
	v_pk_add_f32 v[90:91], v[90:91], v[110:111]
	v_cndmask_b32_e32 v86, v220, v86, vcc
	v_cmp_lt_i32_e32 vcc, -1, v210
	s_waitcnt lgkmcnt(0)
	v_pk_add_f32 v[92:93], v[92:93], v[112:113]
	v_cndmask_b32_e32 v87, v220, v87, vcc
	v_cmp_lt_i32_e32 vcc, -1, v213
	s_nop 1
	v_cndmask_b32_e32 v88, v220, v88, vcc
	v_cmp_lt_i32_e32 vcc, -1, v212
	s_nop 1
	v_cndmask_b32_e32 v89, v220, v89, vcc
	v_cmp_lt_i32_e32 vcc, -1, v215
	s_nop 1
	v_cndmask_b32_e32 v90, v220, v90, vcc
	v_cmp_lt_i32_e32 vcc, -1, v214
	s_nop 1
	v_cndmask_b32_e32 v91, v220, v91, vcc
	v_cmp_lt_i32_e32 vcc, -1, v217
	s_nop 1
	v_cndmask_b32_e32 v92, v220, v92, vcc
	v_cmp_lt_i32_e32 vcc, -1, v216
	s_nop 1
	v_cndmask_b32_e32 v93, v220, v93, vcc

; template <int MODE, int DK, bool PASS2> ...
;     ...
; #pragma unroll
;                     for (int r = 0; r < 16; ++r) { s0[r] *= sl2; s1[r] *= sl2; }
;                     if (need_bias || need_causal || need_win) {
; #pragma unroll
;                         for (int i = 0; i < 32; ++i) {
;                             const int s = kv0 + (i >> 3) * 16 + 8 * g + (i & 7);
;                             const int dist = t_lane - ((MODE == M_CMP) ? 16 * s + 31 : s);
;                             float v = (i < 16) ? s0[i & 15] : s1[i & 15];
;                             if (need_bias) { const int di = dist < 0 ? 0 : (dist > 128 ? 128 : dist); v += tb[di]; }
;                             bool msk = dist < 0;
;                             if (MODE == M_WIN) msk = msk || dist >= 512;
;                             if (msk) v = NEG;
;                             if (i < 16) s0[i & 15] = v; else s1[i & 15] = v;
;                             if ((i & 7) == 7) __builtin_amdgcn_sched_barrier(0);
;                         }
;                     }
.LBB0_2603:
	s_andn2_saveexec_b64 s[48:49], s[48:49]
	s_cbranch_execz .LBB0_2609
	s_setprio 1
	v_pk_mul_f32 v[4:5], v[98:99], s[24:25] op_sel_hi:[1,0]
	s_nop 0
	v_pk_mul_f32 v[8:9], v[82:83], s[24:25] op_sel_hi:[1,0]
	v_pk_mul_f32 v[6:7], v[100:101], s[24:25] op_sel_hi:[1,0]
	v_pk_mul_f32 v[12:13], v[84:85], s[24:25] op_sel_hi:[1,0]
	v_pk_mul_f32 v[10:11], v[102:103], s[24:25] op_sel_hi:[1,0]
	v_pk_mul_f32 v[16:17], v[86:87], s[24:25] op_sel_hi:[1,0]
	v_pk_mul_f32 v[14:15], v[104:105], s[24:25] op_sel_hi:[1,0]
	v_pk_mul_f32 v[84:85], v[88:89], s[24:25] op_sel_hi:[1,0]
	v_pk_mul_f32 v[82:83], v[106:107], s[24:25] op_sel_hi:[1,0]
	v_pk_mul_f32 v[88:89], v[90:91], s[24:25] op_sel_hi:[1,0]
	v_pk_mul_f32 v[86:87], v[108:109], s[24:25] op_sel_hi:[1,0]
	v_pk_mul_f32 v[92:93], v[92:93], s[24:25] op_sel_hi:[1,0]
	v_pk_mul_f32 v[90:91], v[110:111], s[24:25] op_sel_hi:[1,0]
	v_pk_mul_f32 v[98:99], v[94:95], s[24:25] op_sel_hi:[1,0]
	v_pk_mul_f32 v[94:95], v[112:113], s[24:25] op_sel_hi:[1,0]
	v_pk_mul_f32 v[96:97], v[96:97], s[24:25] op_sel_hi:[1,0]
	s_and_saveexec_b64 s[50:51], s[6:7]
	s_cbranch_execz .LBB0_2606
	v_subrev_u32_e32 v100, s78, v211
	v_add_u32_e32 v176, v100, v1
	v_add_u32_e32 v177, v100, v172
	v_add_u32_e32 v178, v100, v165
	v_add_u32_e32 v179, v100, v166
	v_add_u32_e32 v180, v100, v167
	v_add_u32_e32 v181, v100, v168
	v_add_u32_e32 v183, v100, v170
	v_med3_i32 v101, v177, 0, v196
	s_add_i32 s6, s58, 0x100
	v_med3_i32 v102, v176, 0, v196
	v_med3_i32 v103, v179, 0, v196
	v_med3_i32 v104, v178, 0, v196
	v_med3_i32 v105, v181, 0, v196
	v_med3_i32 v106, v180, 0, v196
	v_add_u32_e32 v182, v100, v169
	v_med3_i32 v100, v183, 0, v196
	v_lshl_add_u32 v101, v101, 2, s6
	v_lshl_add_u32 v102, v102, 2, s6
	v_lshl_add_u32 v103, v103, 2, s6
	v_lshl_add_u32 v104, v104, 2, s6
	v_lshl_add_u32 v105, v105, 2, s6
	v_lshl_add_u32 v106, v106, 2, s6
	v_lshl_add_u32 v107, v100, 2, s6
	v_med3_i32 v100, v182, 0, v196
	v_lshl_add_u32 v108, v100, 2, s6
	ds_read_b32 v100, v101
	ds_read_b32 v101, v102
	ds_read_b32 v102, v103
	ds_read_b32 v103, v104
	ds_read_b32 v104, v105
	ds_read_b32 v105, v106
	ds_read_b32 v106, v107
	ds_read_b32 v107, v108
	s_waitcnt lgkmcnt(6)
	v_pk_add_f32 v[4:5], v[4:5], v[100:101]
	v_cmp_lt_i32_e32 vcc, -1, v177
	s_waitcnt lgkmcnt(4)
	v_pk_add_f32 v[6:7], v[6:7], v[102:103]
	s_or_b32 s7, s78, 16
	v_cndmask_b32_e32 v4, v194, v4, vcc
	v_cmp_lt_i32_e32 vcc, -1, v176
	v_subrev_u32_e32 v108, s7, v211
	s_waitcnt lgkmcnt(2)
	v_pk_add_f32 v[10:11], v[10:11], v[104:105]
	v_cndmask_b32_e32 v5, v194, v5, vcc
	v_cmp_lt_i32_e32 vcc, -1, v179
	v_add_u32_e32 v184, v108, v1
	v_add_u32_e32 v185, v108, v172
	v_cndmask_b32_e32 v6, v194, v6, vcc
	v_cmp_lt_i32_e32 vcc, -1, v178
	v_add_u32_e32 v186, v108, v165
	v_add_u32_e32 v187, v108, v166
	v_cndmask_b32_e32 v7, v194, v7, vcc
	v_cmp_lt_i32_e32 vcc, -1, v181
	v_add_u32_e32 v188, v108, v167
	v_add_u32_e32 v189, v108, v168
	v_add_u32_e32 v191, v108, v170
	v_cndmask_b32_e32 v10, v194, v10, vcc
	v_cmp_lt_i32_e32 vcc, -1, v180
	v_med3_i32 v109, v185, 0, v196
	v_med3_i32 v110, v184, 0, v196
	v_med3_i32 v111, v187, 0, v196
	v_med3_i32 v112, v186, 0, v196
	v_med3_i32 v113, v189, 0, v196
	v_med3_i32 v174, v188, 0, v196
	v_add_u32_e32 v190, v108, v169
	v_med3_i32 v108, v191, 0, v196
	s_waitcnt lgkmcnt(0)
	v_pk_add_f32 v[14:15], v[14:15], v[106:107]
	v_cndmask_b32_e32 v11, v194, v11, vcc
	v_cmp_lt_i32_e32 vcc, -1, v183
	v_lshl_add_u32 v109, v109, 2, s6
	v_lshl_add_u32 v110, v110, 2, s6
	v_lshl_add_u32 v111, v111, 2, s6
	v_lshl_add_u32 v112, v112, 2, s6
	v_lshl_add_u32 v113, v113, 2, s6
	v_lshl_add_u32 v174, v174, 2, s6
	v_lshl_add_u32 v175, v108, 2, s6
	v_med3_i32 v108, v190, 0, v196
	v_cndmask_b32_e32 v14, v194, v14, vcc
	v_cmp_lt_i32_e32 vcc, -1, v182
	v_lshl_add_u32 v218, v108, 2, s6
	ds_read_b32 v108, v109
	ds_read_b32 v109, v110
	ds_read_b32 v110, v111
	ds_read_b32 v111, v112
	ds_read_b32 v112, v113
	ds_read_b32 v113, v174
	ds_read_b32 v174, v175
	ds_read_b32 v175, v218
	s_waitcnt lgkmcnt(6)
	v_pk_add_f32 v[82:83], v[82:83], v[108:109]
	v_cndmask_b32_e32 v15, v194, v15, vcc
	v_cmp_lt_i32_e32 vcc, -1, v185
	s_waitcnt lgkmcnt(4)
	v_pk_add_f32 v[86:87], v[86:87], v[110:111]
	s_waitcnt lgkmcnt(2)
	v_pk_add_f32 v[90:91], v[90:91], v[112:113]
	v_cndmask_b32_e32 v82, v194, v82, vcc
	v_cmp_lt_i32_e32 vcc, -1, v184
	s_waitcnt lgkmcnt(0)
; template <int MODE, int DK, bool PASS2> ...
;     ...
;                     if (need_bias || need_causal || need_win) {
; #pragma unroll
;                         for (int i = 0; i < 32; ++i) {
;                             const int s = kv0 + (i >> 3) * 16 + 8 * g + (i & 7);
;                             const int dist = t_lane - ((MODE == M_CMP) ? 16 * s + 31 : s);
;                             float v = (i < 16) ? s0[i & 15] : s1[i & 15];
;                             if (need_bias) { const int di = dist < 0 ? 0 : (dist > 128 ? 128 : dist); v += tb[di]; }
;                             bool msk = dist < 0;
;                             if (MODE == M_WIN) msk = msk || dist >= 512;
;                             if (msk) v = NEG;
;                             if (i < 16) s0[i & 15] = v; else s1[i & 15] = v;
;                             if ((i & 7) == 7) __builtin_amdgcn_sched_barrier(0);
;                         }
;                     }
	v_pk_add_f32 v[94:95], v[94:95], v[174:175]
	v_cndmask_b32_e32 v83, v194, v83, vcc
	v_cmp_lt_i32_e32 vcc, -1, v187
	s_nop 1
	v_cndmask_b32_e32 v86, v194, v86, vcc
	v_cmp_lt_i32_e32 vcc, -1, v186
	s_nop 1
	v_cndmask_b32_e32 v87, v194, v87, vcc
	v_cmp_lt_i32_e32 vcc, -1, v189
	s_nop 1
	v_cndmask_b32_e32 v90, v194, v90, vcc
	v_cmp_lt_i32_e32 vcc, -1, v188
	s_nop 1
	v_cndmask_b32_e32 v91, v194, v91, vcc
	v_cmp_lt_i32_e32 vcc, -1, v191
	s_nop 1
	v_cndmask_b32_e32 v94, v194, v94, vcc
	v_cmp_lt_i32_e32 vcc, -1, v190
	s_nop 1
	v_cndmask_b32_e32 v95, v194, v95, vcc
	s_or_b32 s7, s78, 32
	v_subrev_u32_e32 v100, s7, v211
	v_add_u32_e32 v176, v100, v1
	v_add_u32_e32 v177, v100, v172
	v_add_u32_e32 v178, v100, v165
	v_add_u32_e32 v179, v100, v166
	v_add_u32_e32 v180, v100, v167
	v_add_u32_e32 v181, v100, v168
	v_add_u32_e32 v183, v100, v170
	v_med3_i32 v101, v177, 0, v196
	v_med3_i32 v102, v176, 0, v196
	v_med3_i32 v103, v179, 0, v196
	v_med3_i32 v104, v178, 0, v196
	v_med3_i32 v105, v181, 0, v196
	v_med3_i32 v106, v180, 0, v196
	v_add_u32_e32 v182, v100, v169
	v_med3_i32 v100, v183, 0, v196
	v_lshl_add_u32 v101, v101, 2, s6
	v_lshl_add_u32 v102, v102, 2, s6
	v_lshl_add_u32 v103, v103, 2, s6
	v_lshl_add_u32 v104, v104, 2, s6
	v_lshl_add_u32 v105, v105, 2, s6
	v_lshl_add_u32 v106, v106, 2, s6
	v_lshl_add_u32 v107, v100, 2, s6
	v_med3_i32 v100, v182, 0, v196
	v_lshl_add_u32 v108, v100, 2, s6
	ds_read_b32 v100, v101
	ds_read_b32 v101, v102
	ds_read_b32 v102, v103
	ds_read_b32 v103, v104
	ds_read_b32 v104, v105
	ds_read_b32 v105, v106
	ds_read_b32 v106, v107
	ds_read_b32 v107, v108
	s_waitcnt lgkmcnt(6)
	v_pk_add_f32 v[8:9], v[8:9], v[100:101]
	v_cmp_lt_i32_e32 vcc, -1, v177
	s_waitcnt lgkmcnt(4)
	v_pk_add_f32 v[12:13], v[12:13], v[102:103]
	s_or_b32 s7, s78, 48
	v_cndmask_b32_e32 v8, v194, v8, vcc
	v_cmp_lt_i32_e32 vcc, -1, v176
	v_subrev_u32_e32 v108, s7, v211
	s_waitcnt lgkmcnt(2)
	v_pk_add_f32 v[16:17], v[16:17], v[104:105]
	v_cndmask_b32_e32 v9, v194, v9, vcc
	v_cmp_lt_i32_e32 vcc, -1, v179
	v_add_u32_e32 v184, v108, v1
	v_add_u32_e32 v185, v108, v172
	v_cndmask_b32_e32 v12, v194, v12, vcc
	v_cmp_lt_i32_e32 vcc, -1, v178
	v_add_u32_e32 v186, v108, v165
	v_add_u32_e32 v187, v108, v166
	v_cndmask_b32_e32 v13, v194, v13, vcc
	v_cmp_lt_i32_e32 vcc, -1, v181
	v_add_u32_e32 v188, v108, v167
	v_add_u32_e32 v189, v108, v168
	v_add_u32_e32 v191, v108, v170
	v_cndmask_b32_e32 v16, v194, v16, vcc
	v_cmp_lt_i32_e32 vcc, -1, v180
	v_med3_i32 v109, v185, 0, v196
	v_med3_i32 v110, v184, 0, v196
	v_med3_i32 v111, v187, 0, v196
	v_med3_i32 v112, v186, 0, v196
	v_med3_i32 v113, v189, 0, v196
	v_med3_i32 v174, v188, 0, v196
	v_add_u32_e32 v190, v108, v169
	v_med3_i32 v108, v191, 0, v196
	s_waitcnt lgkmcnt(0)
	v_pk_add_f32 v[84:85], v[84:85], v[106:107]
	v_cndmask_b32_e32 v17, v194, v17, vcc
	v_cmp_lt_i32_e32 vcc, -1, v183
	v_lshl_add_u32 v109, v109, 2, s6
	v_lshl_add_u32 v110, v110, 2, s6
	v_lshl_add_u32 v111, v111, 2, s6
	v_lshl_add_u32 v112, v112, 2, s6
	v_lshl_add_u32 v113, v113, 2, s6
	v_lshl_add_u32 v174, v174, 2, s6
	v_lshl_add_u32 v175, v108, 2, s6
	v_med3_i32 v108, v190, 0, v196
	v_cndmask_b32_e32 v84, v194, v84, vcc
	v_cmp_lt_i32_e32 vcc, -1, v182
	v_lshl_add_u32 v218, v108, 2, s6
	ds_read_b32 v108, v109
	ds_read_b32 v109, v110
	ds_read_b32 v110, v111
	ds_read_b32 v111, v112
	ds_read_b32 v112, v113
	ds_read_b32 v113, v174
	ds_read_b32 v174, v175
	ds_read_b32 v175, v218
	s_waitcnt lgkmcnt(6)
	v_pk_add_f32 v[88:89], v[88:89], v[108:109]
	v_cndmask_b32_e32 v85, v194, v85, vcc
	v_cmp_lt_i32_e32 vcc, -1, v185
	s_waitcnt lgkmcnt(4)
	v_pk_add_f32 v[92:93], v[92:93], v[110:111]
	s_waitcnt lgkmcnt(2)
	v_pk_add_f32 v[98:99], v[98:99], v[112:113]
	v_cndmask_b32_e32 v88, v194, v88, vcc
	v_cmp_lt_i32_e32 vcc, -1, v184
	s_waitcnt lgkmcnt(0)
	v_pk_add_f32 v[96:97], v[96:97], v[174:175]
	v_cndmask_b32_e32 v89, v194, v89, vcc
	v_cmp_lt_i32_e32 vcc, -1, v187
	s_nop 1
	v_cndmask_b32_e32 v92, v194, v92, vcc
	v_cmp_lt_i32_e32 vcc, -1, v186
	s_nop 1
	v_cndmask_b32_e32 v93, v194, v93, vcc
	v_cmp_lt_i32_e32 vcc, -1, v189
	s_nop 1
	v_cndmask_b32_e32 v98, v194, v98, vcc
	v_cmp_lt_i32_e32 vcc, -1, v188
	s_nop 1
	v_cndmask_b32_e32 v99, v194, v99, vcc
	v_cmp_lt_i32_e32 vcc, -1, v191
	s_nop 1
	v_cndmask_b32_e32 v96, v194, v96, vcc
	v_cmp_lt_i32_e32 vcc, -1, v190
	s_nop 1
	v_cndmask_b32_e32 v97, v194, v97, vcc
